# up/down projection LDS-DMA mainloops as rolled 3-stage loops (smaller code) instead of full unroll
# speedup vs baseline: 1.0204x; 1.0016x over previous
.LBB0_1066:
	v_add_co_u32_e32 v182, vcc, 0x800, v152
	s_nop 1
	v_addc_co_u32_e32 v183, vcc, 0, v153, vcc
	v_add_co_u32_e32 v204, vcc, s34, v182
	s_nop 1
	v_addc_co_u32_e32 v205, vcc, 0, v183, vcc
	v_add_co_u32_e32 v206, vcc, s35, v182
	s_nop 1
	v_addc_co_u32_e32 v207, vcc, 0, v183, vcc
	v_add_co_u32_e32 v208, vcc, 0x14fe000, v154
	s_nop 1
	v_addc_co_u32_e32 v209, vcc, 0, v155, vcc
	v_add_co_u32_e32 v210, vcc, 0x1520000, v154
	s_nop 1
	v_addc_co_u32_e32 v211, vcc, 0, v155, vcc
	v_add_co_u32_e32 v212, vcc, 0x1542000, v154
	s_nop 1
	v_addc_co_u32_e32 v213, vcc, 0, v155, vcc
	v_add_co_u32_e32 v214, vcc, 0x1564000, v154
	s_nop 1
	v_addc_co_u32_e32 v215, vcc, 0, v155, vcc
	v_and_b32_e32 v216, 3, v156
	v_bfe_u32 v217, v156, 4, 2
	v_xor_b32_e32 v218, v216, v217
	v_sub_u32_e32 v218, v218, v216
	v_lshlrev_b32_e32 v218, 4, v218
	v_ashrrev_i32_e32 v219, 31, v218
	v_lshl_add_u64 v[204:205], v[218:219], 0, v[204:205]
	v_lshl_add_u64 v[206:207], v[218:219], 0, v[206:207]
	v_lshl_add_u64 v[208:209], v[218:219], 0, v[208:209]
	v_lshl_add_u64 v[210:211], v[218:219], 0, v[210:211]
	v_lshl_add_u64 v[212:213], v[218:219], 0, v[212:213]
	v_lshl_add_u64 v[214:215], v[218:219], 0, v[214:215]
	v_mov_b32_e32 v216, 64
	v_mov_b32_e32 v217, 0
	v_lshl_add_u64 v[204:205], v[216:217], 1, v[204:205]
	v_lshl_add_u64 v[206:207], v[216:217], 1, v[206:207]
	v_lshl_add_u64 v[208:209], v[216:217], 1, v[208:209]
	v_lshl_add_u64 v[210:211], v[216:217], 1, v[210:211]
	v_lshl_add_u64 v[212:213], v[216:217], 1, v[212:213]
	v_lshl_add_u64 v[214:215], v[216:217], 1, v[214:215]
	v_lshrrev_b32_e32 v246, 6, v156
	v_lshlrev_b32_e32 v246, 10, v246
	s_nop 0
	v_readfirstlane_b32 s14, v246
	ds_read_b128 v[162:165], v159 offset:8192
	ds_read_b128 v[178:181], v158
	ds_read_b128 v[166:169], v159 offset:10240
	ds_read_b128 v[200:203], v158 offset:2048
	ds_read_b128 v[170:173], v159 offset:12288
	ds_read_b128 v[174:177], v159 offset:14336
	s_waitcnt lgkmcnt(4)
	v_mfma_f32_32x32x16_bf16 v[112:127], v[162:165], v[178:181], v[112:127]
	s_waitcnt lgkmcnt(3)
	v_mfma_f32_32x32x16_bf16 v[96:111], v[166:169], v[178:181], v[96:111]
	s_waitcnt lgkmcnt(1)
	v_mfma_f32_32x32x16_bf16 v[80:95], v[170:173], v[178:181], v[80:95]
	s_waitcnt lgkmcnt(0)
	v_mfma_f32_32x32x16_bf16 v[64:79], v[174:177], v[178:181], v[64:79]
	v_mfma_f32_32x32x16_bf16 v[48:63], v[162:165], v[200:203], v[48:63]
	v_mfma_f32_32x32x16_bf16 v[32:47], v[166:169], v[200:203], v[32:47]
	v_mfma_f32_32x32x16_bf16 v[16:31], v[170:173], v[200:203], v[16:31]
	v_mfma_f32_32x32x16_bf16 v[0:15], v[174:177], v[200:203], v[0:15]
	ds_read_b128 v[162:165], v157 offset:8192
	ds_read_b128 v[178:181], v160
	ds_read_b128 v[166:169], v157 offset:10240
	ds_read_b128 v[200:203], v160 offset:2048
	ds_read_b128 v[170:173], v157 offset:12288
	ds_read_b128 v[174:177], v157 offset:14336
	s_waitcnt vmcnt(5)
	ds_write_b128 v161, v[144:147] offset:24576
	s_waitcnt vmcnt(3)
	ds_write_b128 v161, v[148:151] offset:28672
	ds_write_b128 v161, v[140:143] offset:32768
	s_waitcnt vmcnt(2)
	ds_write_b128 v161, v[132:135] offset:36864
	s_waitcnt vmcnt(1)
	ds_write_b128 v161, v[128:131] offset:40960
	s_waitcnt vmcnt(0)
	ds_write_b128 v161, v[136:139] offset:45056
	s_add_u32 m0, s14, 0xc000
	s_nop 0
	global_load_lds_dwordx4 v[204:205], off
	v_lshl_add_u64 v[204:205], v[216:217], 0, v[204:205]
	s_add_u32 m0, s14, 0xd000
	s_nop 0
	global_load_lds_dwordx4 v[206:207], off
	v_lshl_add_u64 v[206:207], v[216:217], 0, v[206:207]
	s_add_u32 m0, s14, 0xe000
	s_nop 0
	global_load_lds_dwordx4 v[208:209], off
	v_lshl_add_u64 v[208:209], v[216:217], 0, v[208:209]
	s_add_u32 m0, s14, 0xf000
	s_nop 0
	global_load_lds_dwordx4 v[210:211], off
	v_lshl_add_u64 v[210:211], v[216:217], 0, v[210:211]
	s_add_u32 m0, s14, 0x10000
	s_nop 0
	global_load_lds_dwordx4 v[212:213], off
	v_lshl_add_u64 v[212:213], v[216:217], 0, v[212:213]
	s_add_u32 m0, s14, 0x11000
	s_nop 0
	global_load_lds_dwordx4 v[214:215], off
	v_lshl_add_u64 v[214:215], v[216:217], 0, v[214:215]
	s_waitcnt lgkmcnt(10)
	v_mfma_f32_32x32x16_bf16 v[112:127], v[162:165], v[178:181], v[112:127]
	s_waitcnt lgkmcnt(9)
	v_mfma_f32_32x32x16_bf16 v[96:111], v[166:169], v[178:181], v[96:111]
	s_waitcnt lgkmcnt(7)
	v_mfma_f32_32x32x16_bf16 v[80:95], v[170:173], v[178:181], v[80:95]
	s_waitcnt lgkmcnt(6)
	v_mfma_f32_32x32x16_bf16 v[64:79], v[174:177], v[178:181], v[64:79]
	v_mfma_f32_32x32x16_bf16 v[48:63], v[162:165], v[200:203], v[48:63]
	v_mfma_f32_32x32x16_bf16 v[32:47], v[166:169], v[200:203], v[32:47]
	v_mfma_f32_32x32x16_bf16 v[16:31], v[170:173], v[200:203], v[16:31]
	v_mfma_f32_32x32x16_bf16 v[0:15], v[174:177], v[200:203], v[0:15]
	s_waitcnt lgkmcnt(0)
	s_barrier
	s_mov_b32 s15, 0
.Lup_dma_loop:
	ds_read_b128 v[162:165], v159 offset:32768
	ds_read_b128 v[178:181], v158 offset:24576
	ds_read_b128 v[166:169], v159 offset:34816
	ds_read_b128 v[200:203], v158 offset:26624
	ds_read_b128 v[170:173], v159 offset:36864
	ds_read_b128 v[174:177], v159 offset:38912
	ds_read_b128 v[128:131], v157 offset:32768
	ds_read_b128 v[144:147], v160 offset:24576
	ds_read_b128 v[132:135], v157 offset:34816
	ds_read_b128 v[148:151], v160 offset:26624
	ds_read_b128 v[136:139], v157 offset:36864
	ds_read_b128 v[140:143], v157 offset:38912
	s_waitcnt lgkmcnt(10)
	v_mfma_f32_32x32x16_bf16 v[112:127], v[162:165], v[178:181], v[112:127]
	s_mov_b32 m0, s14
	s_nop 0
	global_load_lds_dwordx4 v[204:205], off
	v_lshl_add_u64 v[204:205], v[216:217], 0, v[204:205]
	s_waitcnt lgkmcnt(9)
	v_mfma_f32_32x32x16_bf16 v[96:111], v[166:169], v[178:181], v[96:111]
	s_add_u32 m0, s14, 0x1000
	s_nop 0
	global_load_lds_dwordx4 v[206:207], off
	v_lshl_add_u64 v[206:207], v[216:217], 0, v[206:207]
	s_waitcnt lgkmcnt(7)
	v_mfma_f32_32x32x16_bf16 v[80:95], v[170:173], v[178:181], v[80:95]
	s_add_u32 m0, s14, 0x2000
	s_nop 0
	global_load_lds_dwordx4 v[208:209], off
	v_lshl_add_u64 v[208:209], v[216:217], 0, v[208:209]
	s_waitcnt lgkmcnt(6)
	v_mfma_f32_32x32x16_bf16 v[64:79], v[174:177], v[178:181], v[64:79]
	s_add_u32 m0, s14, 0x3000
	s_nop 0
	global_load_lds_dwordx4 v[210:211], off
	v_lshl_add_u64 v[210:211], v[216:217], 0, v[210:211]
	v_mfma_f32_32x32x16_bf16 v[48:63], v[162:165], v[200:203], v[48:63]
	s_add_u32 m0, s14, 0x4000
	s_nop 0
	global_load_lds_dwordx4 v[212:213], off
	v_lshl_add_u64 v[212:213], v[216:217], 0, v[212:213]
	v_mfma_f32_32x32x16_bf16 v[32:47], v[166:169], v[200:203], v[32:47]
	s_add_u32 m0, s14, 0x5000
	s_nop 0
	global_load_lds_dwordx4 v[214:215], off
	v_lshl_add_u64 v[214:215], v[216:217], 0, v[214:215]
	v_mfma_f32_32x32x16_bf16 v[16:31], v[170:173], v[200:203], v[16:31]
	v_mfma_f32_32x32x16_bf16 v[0:15], v[174:177], v[200:203], v[0:15]
	s_waitcnt lgkmcnt(4)
	v_mfma_f32_32x32x16_bf16 v[112:127], v[128:131], v[144:147], v[112:127]
	s_waitcnt lgkmcnt(3)
	v_mfma_f32_32x32x16_bf16 v[96:111], v[132:135], v[144:147], v[96:111]
	s_waitcnt lgkmcnt(1)
	v_mfma_f32_32x32x16_bf16 v[80:95], v[136:139], v[144:147], v[80:95]
	s_waitcnt lgkmcnt(0)
	v_mfma_f32_32x32x16_bf16 v[64:79], v[140:143], v[144:147], v[64:79]
	v_mfma_f32_32x32x16_bf16 v[48:63], v[128:131], v[148:151], v[48:63]
	v_mfma_f32_32x32x16_bf16 v[32:47], v[132:135], v[148:151], v[32:47]
	v_mfma_f32_32x32x16_bf16 v[16:31], v[136:139], v[148:151], v[16:31]
	v_mfma_f32_32x32x16_bf16 v[0:15], v[140:143], v[148:151], v[0:15]
	s_waitcnt vmcnt(6)
	s_waitcnt lgkmcnt(0)
	s_barrier
	ds_read_b128 v[162:165], v159 offset:57344
	ds_read_b128 v[178:181], v158 offset:49152
	ds_read_b128 v[166:169], v159 offset:59392
	ds_read_b128 v[200:203], v158 offset:51200
	ds_read_b128 v[170:173], v159 offset:61440
	ds_read_b128 v[174:177], v159 offset:63488
	ds_read_b128 v[128:131], v157 offset:57344
	ds_read_b128 v[144:147], v160 offset:49152
	ds_read_b128 v[132:135], v157 offset:59392
	ds_read_b128 v[148:151], v160 offset:51200
	ds_read_b128 v[136:139], v157 offset:61440
	ds_read_b128 v[140:143], v157 offset:63488
	s_waitcnt lgkmcnt(10)
	v_mfma_f32_32x32x16_bf16 v[112:127], v[162:165], v[178:181], v[112:127]
	s_add_u32 m0, s14, 0x6000
	s_nop 0
	global_load_lds_dwordx4 v[204:205], off
	v_lshl_add_u64 v[204:205], v[216:217], 0, v[204:205]
	s_waitcnt lgkmcnt(9)
	v_mfma_f32_32x32x16_bf16 v[96:111], v[166:169], v[178:181], v[96:111]
	s_add_u32 m0, s14, 0x7000
	s_nop 0
	global_load_lds_dwordx4 v[206:207], off
	v_lshl_add_u64 v[206:207], v[216:217], 0, v[206:207]
	s_waitcnt lgkmcnt(7)
	v_mfma_f32_32x32x16_bf16 v[80:95], v[170:173], v[178:181], v[80:95]
	s_add_u32 m0, s14, 0x8000
	s_nop 0
	global_load_lds_dwordx4 v[208:209], off
	v_lshl_add_u64 v[208:209], v[216:217], 0, v[208:209]
	s_waitcnt lgkmcnt(6)
	v_mfma_f32_32x32x16_bf16 v[64:79], v[174:177], v[178:181], v[64:79]
	s_add_u32 m0, s14, 0x9000
	s_nop 0
	global_load_lds_dwordx4 v[210:211], off
	v_lshl_add_u64 v[210:211], v[216:217], 0, v[210:211]
	v_mfma_f32_32x32x16_bf16 v[48:63], v[162:165], v[200:203], v[48:63]
	s_add_u32 m0, s14, 0xa000
	s_nop 0
	global_load_lds_dwordx4 v[212:213], off
	v_lshl_add_u64 v[212:213], v[216:217], 0, v[212:213]
	v_mfma_f32_32x32x16_bf16 v[32:47], v[166:169], v[200:203], v[32:47]
	s_add_u32 m0, s14, 0xb000
	s_nop 0
	global_load_lds_dwordx4 v[214:215], off
	v_lshl_add_u64 v[214:215], v[216:217], 0, v[214:215]
	v_mfma_f32_32x32x16_bf16 v[16:31], v[170:173], v[200:203], v[16:31]
	v_mfma_f32_32x32x16_bf16 v[0:15], v[174:177], v[200:203], v[0:15]
	s_waitcnt lgkmcnt(4)
	v_mfma_f32_32x32x16_bf16 v[112:127], v[128:131], v[144:147], v[112:127]
	s_waitcnt lgkmcnt(3)
	v_mfma_f32_32x32x16_bf16 v[96:111], v[132:135], v[144:147], v[96:111]
	s_waitcnt lgkmcnt(1)
	v_mfma_f32_32x32x16_bf16 v[80:95], v[136:139], v[144:147], v[80:95]
	s_waitcnt lgkmcnt(0)
	v_mfma_f32_32x32x16_bf16 v[64:79], v[140:143], v[144:147], v[64:79]
	v_mfma_f32_32x32x16_bf16 v[48:63], v[128:131], v[148:151], v[48:63]
	v_mfma_f32_32x32x16_bf16 v[32:47], v[132:135], v[148:151], v[32:47]
	v_mfma_f32_32x32x16_bf16 v[16:31], v[136:139], v[148:151], v[16:31]
	v_mfma_f32_32x32x16_bf16 v[0:15], v[140:143], v[148:151], v[0:15]
	s_waitcnt vmcnt(6)
	s_waitcnt lgkmcnt(0)
	s_barrier
	ds_read_b128 v[162:165], v159 offset:8192
	ds_read_b128 v[178:181], v158
	ds_read_b128 v[166:169], v159 offset:10240
	ds_read_b128 v[200:203], v158 offset:2048
	ds_read_b128 v[170:173], v159 offset:12288
	ds_read_b128 v[174:177], v159 offset:14336
	ds_read_b128 v[128:131], v157 offset:8192
	ds_read_b128 v[144:147], v160
	ds_read_b128 v[132:135], v157 offset:10240
	ds_read_b128 v[148:151], v160 offset:2048
	ds_read_b128 v[136:139], v157 offset:12288
	ds_read_b128 v[140:143], v157 offset:14336
	s_waitcnt lgkmcnt(10)
	v_mfma_f32_32x32x16_bf16 v[112:127], v[162:165], v[178:181], v[112:127]
	s_add_u32 m0, s14, 0xc000
	s_nop 0
	global_load_lds_dwordx4 v[204:205], off
	v_lshl_add_u64 v[204:205], v[216:217], 0, v[204:205]
	s_waitcnt lgkmcnt(9)
	v_mfma_f32_32x32x16_bf16 v[96:111], v[166:169], v[178:181], v[96:111]
	s_add_u32 m0, s14, 0xd000
	s_nop 0
	global_load_lds_dwordx4 v[206:207], off
	v_lshl_add_u64 v[206:207], v[216:217], 0, v[206:207]
	s_waitcnt lgkmcnt(7)
	v_mfma_f32_32x32x16_bf16 v[80:95], v[170:173], v[178:181], v[80:95]
	s_add_u32 m0, s14, 0xe000
	s_nop 0
	global_load_lds_dwordx4 v[208:209], off
	v_lshl_add_u64 v[208:209], v[216:217], 0, v[208:209]
	s_waitcnt lgkmcnt(6)
	v_mfma_f32_32x32x16_bf16 v[64:79], v[174:177], v[178:181], v[64:79]
	s_add_u32 m0, s14, 0xf000
	s_nop 0
	global_load_lds_dwordx4 v[210:211], off
	v_lshl_add_u64 v[210:211], v[216:217], 0, v[210:211]
	v_mfma_f32_32x32x16_bf16 v[48:63], v[162:165], v[200:203], v[48:63]
	s_add_u32 m0, s14, 0x10000
	s_nop 0
	global_load_lds_dwordx4 v[212:213], off
	v_lshl_add_u64 v[212:213], v[216:217], 0, v[212:213]
	v_mfma_f32_32x32x16_bf16 v[32:47], v[166:169], v[200:203], v[32:47]
	s_add_u32 m0, s14, 0x11000
	s_nop 0
	global_load_lds_dwordx4 v[214:215], off
	v_lshl_add_u64 v[214:215], v[216:217], 0, v[214:215]
	v_mfma_f32_32x32x16_bf16 v[16:31], v[170:173], v[200:203], v[16:31]
	v_mfma_f32_32x32x16_bf16 v[0:15], v[174:177], v[200:203], v[0:15]
	s_waitcnt lgkmcnt(4)
	v_mfma_f32_32x32x16_bf16 v[112:127], v[128:131], v[144:147], v[112:127]
	s_waitcnt lgkmcnt(3)
	v_mfma_f32_32x32x16_bf16 v[96:111], v[132:135], v[144:147], v[96:111]
	s_waitcnt lgkmcnt(1)
	v_mfma_f32_32x32x16_bf16 v[80:95], v[136:139], v[144:147], v[80:95]
	s_waitcnt lgkmcnt(0)
	v_mfma_f32_32x32x16_bf16 v[64:79], v[140:143], v[144:147], v[64:79]
	v_mfma_f32_32x32x16_bf16 v[48:63], v[128:131], v[148:151], v[48:63]
	v_mfma_f32_32x32x16_bf16 v[32:47], v[132:135], v[148:151], v[32:47]
	v_mfma_f32_32x32x16_bf16 v[16:31], v[136:139], v[148:151], v[16:31]
	v_mfma_f32_32x32x16_bf16 v[0:15], v[140:143], v[148:151], v[0:15]
	s_waitcnt vmcnt(6)
	s_waitcnt lgkmcnt(0)
	s_barrier
	s_add_u32 s15, s15, 1
	s_cmp_lg_u32 s15, 9
	s_cbranch_scc1 .Lup_dma_loop
	ds_read_b128 v[162:165], v159 offset:32768
	ds_read_b128 v[178:181], v158 offset:24576
	ds_read_b128 v[166:169], v159 offset:34816
	ds_read_b128 v[200:203], v158 offset:26624
	ds_read_b128 v[170:173], v159 offset:36864
	ds_read_b128 v[174:177], v159 offset:38912
	ds_read_b128 v[128:131], v157 offset:32768
	ds_read_b128 v[144:147], v160 offset:24576
	ds_read_b128 v[132:135], v157 offset:34816
	ds_read_b128 v[148:151], v160 offset:26624
	ds_read_b128 v[136:139], v157 offset:36864
	ds_read_b128 v[140:143], v157 offset:38912
	s_waitcnt lgkmcnt(10)
	v_mfma_f32_32x32x16_bf16 v[112:127], v[162:165], v[178:181], v[112:127]
	s_mov_b32 m0, s14
	s_nop 0
	global_load_lds_dwordx4 v[204:205], off
	v_lshl_add_u64 v[204:205], v[216:217], 0, v[204:205]
	s_waitcnt lgkmcnt(9)
	v_mfma_f32_32x32x16_bf16 v[96:111], v[166:169], v[178:181], v[96:111]
	s_add_u32 m0, s14, 0x1000
	s_nop 0
	global_load_lds_dwordx4 v[206:207], off
	v_lshl_add_u64 v[206:207], v[216:217], 0, v[206:207]
	s_waitcnt lgkmcnt(7)
	v_mfma_f32_32x32x16_bf16 v[80:95], v[170:173], v[178:181], v[80:95]
	s_add_u32 m0, s14, 0x2000
	s_nop 0
	global_load_lds_dwordx4 v[208:209], off
	v_lshl_add_u64 v[208:209], v[216:217], 0, v[208:209]
	s_waitcnt lgkmcnt(6)
	v_mfma_f32_32x32x16_bf16 v[64:79], v[174:177], v[178:181], v[64:79]
	s_add_u32 m0, s14, 0x3000
	s_nop 0
	global_load_lds_dwordx4 v[210:211], off
	v_lshl_add_u64 v[210:211], v[216:217], 0, v[210:211]
	v_mfma_f32_32x32x16_bf16 v[48:63], v[162:165], v[200:203], v[48:63]
	s_add_u32 m0, s14, 0x4000
	s_nop 0
	global_load_lds_dwordx4 v[212:213], off
	v_lshl_add_u64 v[212:213], v[216:217], 0, v[212:213]
	v_mfma_f32_32x32x16_bf16 v[32:47], v[166:169], v[200:203], v[32:47]
	s_add_u32 m0, s14, 0x5000
	s_nop 0
	global_load_lds_dwordx4 v[214:215], off
	v_lshl_add_u64 v[214:215], v[216:217], 0, v[214:215]
	v_mfma_f32_32x32x16_bf16 v[16:31], v[170:173], v[200:203], v[16:31]
	v_mfma_f32_32x32x16_bf16 v[0:15], v[174:177], v[200:203], v[0:15]
	s_waitcnt lgkmcnt(4)
	v_mfma_f32_32x32x16_bf16 v[112:127], v[128:131], v[144:147], v[112:127]
	s_waitcnt lgkmcnt(3)
	v_mfma_f32_32x32x16_bf16 v[96:111], v[132:135], v[144:147], v[96:111]
	s_waitcnt lgkmcnt(1)
	v_mfma_f32_32x32x16_bf16 v[80:95], v[136:139], v[144:147], v[80:95]
	s_waitcnt lgkmcnt(0)
	v_mfma_f32_32x32x16_bf16 v[64:79], v[140:143], v[144:147], v[64:79]
	v_mfma_f32_32x32x16_bf16 v[48:63], v[128:131], v[148:151], v[48:63]
	v_mfma_f32_32x32x16_bf16 v[32:47], v[132:135], v[148:151], v[32:47]
	v_mfma_f32_32x32x16_bf16 v[16:31], v[136:139], v[148:151], v[16:31]
	v_mfma_f32_32x32x16_bf16 v[0:15], v[140:143], v[148:151], v[0:15]
	s_waitcnt vmcnt(6)
	s_waitcnt lgkmcnt(0)
	s_barrier
	ds_read_b128 v[162:165], v159 offset:57344
	ds_read_b128 v[178:181], v158 offset:49152
	ds_read_b128 v[166:169], v159 offset:59392
	ds_read_b128 v[200:203], v158 offset:51200
	ds_read_b128 v[170:173], v159 offset:61440
	ds_read_b128 v[174:177], v159 offset:63488
	ds_read_b128 v[128:131], v157 offset:57344
	ds_read_b128 v[144:147], v160 offset:49152
	ds_read_b128 v[132:135], v157 offset:59392
	ds_read_b128 v[148:151], v160 offset:51200
	ds_read_b128 v[136:139], v157 offset:61440
	ds_read_b128 v[140:143], v157 offset:63488
	s_waitcnt lgkmcnt(10)
	v_mfma_f32_32x32x16_bf16 v[112:127], v[162:165], v[178:181], v[112:127]
	s_add_u32 m0, s14, 0x6000
	s_nop 0
	global_load_lds_dwordx4 v[204:205], off
	v_lshl_add_u64 v[204:205], v[216:217], 0, v[204:205]
	s_waitcnt lgkmcnt(9)
	v_mfma_f32_32x32x16_bf16 v[96:111], v[166:169], v[178:181], v[96:111]
	s_add_u32 m0, s14, 0x7000
	s_nop 0
	global_load_lds_dwordx4 v[206:207], off
	v_lshl_add_u64 v[206:207], v[216:217], 0, v[206:207]
	s_waitcnt lgkmcnt(7)
	v_mfma_f32_32x32x16_bf16 v[80:95], v[170:173], v[178:181], v[80:95]
	s_add_u32 m0, s14, 0x8000
	s_nop 0
	global_load_lds_dwordx4 v[208:209], off
	v_lshl_add_u64 v[208:209], v[216:217], 0, v[208:209]
	s_waitcnt lgkmcnt(6)
	v_mfma_f32_32x32x16_bf16 v[64:79], v[174:177], v[178:181], v[64:79]
	s_add_u32 m0, s14, 0x9000
	s_nop 0
	global_load_lds_dwordx4 v[210:211], off
	v_lshl_add_u64 v[210:211], v[216:217], 0, v[210:211]
	v_mfma_f32_32x32x16_bf16 v[48:63], v[162:165], v[200:203], v[48:63]
	s_add_u32 m0, s14, 0xa000
	s_nop 0
	global_load_lds_dwordx4 v[212:213], off
	v_lshl_add_u64 v[212:213], v[216:217], 0, v[212:213]
	v_mfma_f32_32x32x16_bf16 v[32:47], v[166:169], v[200:203], v[32:47]
	s_add_u32 m0, s14, 0xb000
	s_nop 0
	global_load_lds_dwordx4 v[214:215], off
	v_lshl_add_u64 v[214:215], v[216:217], 0, v[214:215]
	v_mfma_f32_32x32x16_bf16 v[16:31], v[170:173], v[200:203], v[16:31]
	v_mfma_f32_32x32x16_bf16 v[0:15], v[174:177], v[200:203], v[0:15]
	s_waitcnt lgkmcnt(4)
	v_mfma_f32_32x32x16_bf16 v[112:127], v[128:131], v[144:147], v[112:127]
	s_waitcnt lgkmcnt(3)
	v_mfma_f32_32x32x16_bf16 v[96:111], v[132:135], v[144:147], v[96:111]
	s_waitcnt lgkmcnt(1)
	v_mfma_f32_32x32x16_bf16 v[80:95], v[136:139], v[144:147], v[80:95]
	s_waitcnt lgkmcnt(0)
	v_mfma_f32_32x32x16_bf16 v[64:79], v[140:143], v[144:147], v[64:79]
	v_mfma_f32_32x32x16_bf16 v[48:63], v[128:131], v[148:151], v[48:63]
	v_mfma_f32_32x32x16_bf16 v[32:47], v[132:135], v[148:151], v[32:47]
	v_mfma_f32_32x32x16_bf16 v[16:31], v[136:139], v[148:151], v[16:31]
	v_mfma_f32_32x32x16_bf16 v[0:15], v[140:143], v[148:151], v[0:15]
	s_waitcnt vmcnt(6)
	s_waitcnt lgkmcnt(0)
	s_barrier
	ds_read_b128 v[162:165], v159 offset:8192
	ds_read_b128 v[178:181], v158
	ds_read_b128 v[166:169], v159 offset:10240
	ds_read_b128 v[200:203], v158 offset:2048
	ds_read_b128 v[170:173], v159 offset:12288
	ds_read_b128 v[174:177], v159 offset:14336
	ds_read_b128 v[128:131], v157 offset:8192
	ds_read_b128 v[144:147], v160
	ds_read_b128 v[132:135], v157 offset:10240
	ds_read_b128 v[148:151], v160 offset:2048
	ds_read_b128 v[136:139], v157 offset:12288
	ds_read_b128 v[140:143], v157 offset:14336
	s_waitcnt lgkmcnt(10)
	v_mfma_f32_32x32x16_bf16 v[112:127], v[162:165], v[178:181], v[112:127]
	s_waitcnt lgkmcnt(9)
	v_mfma_f32_32x32x16_bf16 v[96:111], v[166:169], v[178:181], v[96:111]
	s_waitcnt lgkmcnt(7)
	v_mfma_f32_32x32x16_bf16 v[80:95], v[170:173], v[178:181], v[80:95]
	s_waitcnt lgkmcnt(6)
	v_mfma_f32_32x32x16_bf16 v[64:79], v[174:177], v[178:181], v[64:79]
	v_mfma_f32_32x32x16_bf16 v[48:63], v[162:165], v[200:203], v[48:63]
	v_mfma_f32_32x32x16_bf16 v[32:47], v[166:169], v[200:203], v[32:47]
	v_mfma_f32_32x32x16_bf16 v[16:31], v[170:173], v[200:203], v[16:31]
	v_mfma_f32_32x32x16_bf16 v[0:15], v[174:177], v[200:203], v[0:15]
	s_waitcnt lgkmcnt(4)
	v_mfma_f32_32x32x16_bf16 v[112:127], v[128:131], v[144:147], v[112:127]
	s_waitcnt lgkmcnt(3)
	v_mfma_f32_32x32x16_bf16 v[96:111], v[132:135], v[144:147], v[96:111]
	s_waitcnt lgkmcnt(1)
	v_mfma_f32_32x32x16_bf16 v[80:95], v[136:139], v[144:147], v[80:95]
	s_waitcnt lgkmcnt(0)
	v_mfma_f32_32x32x16_bf16 v[64:79], v[140:143], v[144:147], v[64:79]
	v_mfma_f32_32x32x16_bf16 v[48:63], v[128:131], v[148:151], v[48:63]
	v_mfma_f32_32x32x16_bf16 v[32:47], v[132:135], v[148:151], v[32:47]
	v_mfma_f32_32x32x16_bf16 v[16:31], v[136:139], v[148:151], v[16:31]
	v_mfma_f32_32x32x16_bf16 v[0:15], v[140:143], v[148:151], v[0:15]
	s_waitcnt vmcnt(0)
	s_waitcnt lgkmcnt(0)
	s_barrier
	ds_read_b128 v[162:165], v159 offset:32768
	ds_read_b128 v[178:181], v158 offset:24576
	ds_read_b128 v[166:169], v159 offset:34816
	ds_read_b128 v[200:203], v158 offset:26624
	ds_read_b128 v[170:173], v159 offset:36864
	ds_read_b128 v[174:177], v159 offset:38912
	ds_read_b128 v[128:131], v157 offset:32768
	ds_read_b128 v[144:147], v160 offset:24576
	ds_read_b128 v[132:135], v157 offset:34816
	ds_read_b128 v[148:151], v160 offset:26624
	ds_read_b128 v[136:139], v157 offset:36864
	ds_read_b128 v[140:143], v157 offset:38912
	s_waitcnt lgkmcnt(10)
	v_mfma_f32_32x32x16_bf16 v[112:127], v[162:165], v[178:181], v[112:127]
	s_waitcnt lgkmcnt(9)
	v_mfma_f32_32x32x16_bf16 v[96:111], v[166:169], v[178:181], v[96:111]
	s_waitcnt lgkmcnt(7)
	v_mfma_f32_32x32x16_bf16 v[80:95], v[170:173], v[178:181], v[80:95]
	s_waitcnt lgkmcnt(6)
	v_mfma_f32_32x32x16_bf16 v[64:79], v[174:177], v[178:181], v[64:79]
	v_mfma_f32_32x32x16_bf16 v[48:63], v[162:165], v[200:203], v[48:63]
	v_mfma_f32_32x32x16_bf16 v[32:47], v[166:169], v[200:203], v[32:47]
	v_mfma_f32_32x32x16_bf16 v[16:31], v[170:173], v[200:203], v[16:31]
	v_mfma_f32_32x32x16_bf16 v[0:15], v[174:177], v[200:203], v[0:15]
	s_mov_b32 s14, 0xfffffc0
	s_movk_i32 s18, 0x210
	s_lshl_b64 s[4:5], s[4:5], 1
	s_mov_b32 s15, 0
	v_and_b32_e32 v152, 31, v156
	s_waitcnt lgkmcnt(0)
	s_barrier
	v_mfma_f32_32x32x16_bf16 v[48:63], v[128:131], v[148:151], v[48:63]
	v_mfma_f32_32x32x16_bf16 v[0:15], v[140:143], v[148:151], v[0:15]
	s_nop 10
	v_max_f32_e32 v48, v48, v48
	v_max_f32_e32 v49, v49, v49
	v_max_f32_e32 v50, v50, v50
	v_max_f32_e32 v51, v51, v51
	v_max_f32_e32 v52, v52, v52
	v_max_f32_e32 v53, v53, v53
	v_max_f32_e32 v48, 0, v48
	v_mfma_f32_32x32x16_bf16 v[112:127], v[128:131], v[144:147], v[112:127]
	v_lshrrev_b32_e32 v128, 1, v156
	v_lshrrev_b32_e32 v130, 2, v156
	v_and_or_b32 v129, v128, s14, v152
	v_lshlrev_b32_e32 v128, 2, v156
	v_and_b32_e32 v130, 8, v130
	s_movk_i32 s14, 0x100
	v_max_f32_e32 v0, v0, v0
	v_mfma_f32_32x32x16_bf16 v[96:111], v[132:135], v[144:147], v[96:111]
	v_max_f32_e32 v1, v1, v1
	v_max_f32_e32 v2, v2, v2
	v_max_f32_e32 v3, v3, v3
	v_max_f32_e32 v4, v4, v4
	v_max_f32_e32 v5, v5, v5
	v_max_f32_e32 v6, v6, v6
	v_max_f32_e32 v7, v7, v7
	v_mfma_f32_32x32x16_bf16 v[80:95], v[136:139], v[144:147], v[80:95]
	v_and_or_b32 v128, v128, s14, v130
	v_max_f32_e32 v49, 0, v49
	v_max_f32_e32 v50, 0, v50
	v_max_f32_e32 v51, 0, v51
	v_max_f32_e32 v52, 0, v52
	v_max_f32_e32 v53, 0, v53
	v_max_f32_e32 v0, 0, v0
	v_mfma_f32_32x32x16_bf16 v[64:79], v[140:143], v[144:147], v[64:79]
	v_max_f32_e32 v1, 0, v1
	v_max_f32_e32 v2, 0, v2
	v_max_f32_e32 v3, 0, v3
	v_max_f32_e32 v4, 0, v4
	v_max_f32_e32 v5, 0, v5
	v_max_f32_e32 v6, 0, v6
	v_max_f32_e32 v7, 0, v7
	v_mfma_f32_32x32x16_bf16 v[32:47], v[132:135], v[148:151], v[32:47]
	v_max_f32_e32 v8, v8, v8
	v_max_f32_e32 v9, v9, v9
	v_max_f32_e32 v10, v10, v10
	v_max_f32_e32 v11, v11, v11
	v_max_f32_e32 v12, v12, v12
	v_max_f32_e32 v13, v13, v13
	v_max_f32_e32 v14, v14, v14
	v_mfma_f32_32x32x16_bf16 v[16:31], v[136:139], v[148:151], v[16:31]
	v_max_f32_e32 v15, v15, v15
	v_mad_u64_u32 v[128:129], s[14:15], v129, s18, v[128:129]
	v_mul_f32_e64 v48, v48, v48
	v_mul_f32_e64 v49, v49, v49
	v_mul_f32_e64 v50, v50, v50
	v_mul_f32_e64 v51, v51, v51
	v_pk_mul_f32 v[52:53], v[52:53], v[52:53]
	v_pk_mul_f32 v[0:1], v[0:1], v[0:1]
	v_pk_mul_f32 v[2:3], v[2:3], v[2:3]
	v_pk_mul_f32 v[4:5], v[4:5], v[4:5]
	v_pk_mul_f32 v[6:7], v[6:7], v[6:7]
	v_max_f32_e32 v8, 0, v8
	v_max_f32_e32 v9, 0, v9
	v_max_f32_e32 v10, 0, v10
	v_max_f32_e32 v11, 0, v11
	v_max_f32_e32 v12, 0, v12
	v_max_f32_e32 v13, 0, v13
	v_max_f32_e32 v14, 0, v14
	v_max_f32_e32 v15, 0, v15
	v_cvt_pk_bf16_f32 v48, v48, v49
	v_cvt_pk_bf16_f32 v49, v50, v51
	v_cvt_pk_bf16_f32 v50, v52, v53
	v_add_u32_e32 v52, 0x4000, v128
	v_pk_mul_f32 v[8:9], v[8:9], v[8:9]
	v_pk_mul_f32 v[10:11], v[10:11], v[10:11]
	v_pk_mul_f32 v[12:13], v[12:13], v[12:13]
	v_pk_mul_f32 v[14:15], v[14:15], v[14:15]
	v_cvt_pk_bf16_f32 v0, v0, v1
	v_cvt_pk_bf16_f32 v1, v2, v3
	v_cvt_pk_bf16_f32 v2, v4, v5
	v_cvt_pk_bf16_f32 v3, v6, v7
	v_max_f32_e32 v112, v112, v112
	v_max_f32_e32 v113, v113, v113
	v_max_f32_e32 v114, v114, v114
	v_max_f32_e32 v115, v115, v115
	v_max_f32_e32 v116, v116, v116
	v_max_f32_e32 v117, v117, v117
	v_max_f32_e32 v118, v118, v118
	v_max_f32_e32 v119, v119, v119
	v_max_f32_e32 v96, v96, v96
	v_max_f32_e32 v97, v97, v97
	v_max_f32_e32 v98, v98, v98
	v_max_f32_e32 v99, v99, v99
	v_max_f32_e32 v100, v100, v100
	v_max_f32_e32 v101, v101, v101
	v_max_f32_e32 v102, v102, v102
	v_max_f32_e32 v103, v103, v103
	v_max_f32_e32 v80, v80, v80
	v_max_f32_e32 v81, v81, v81
	v_max_f32_e32 v82, v82, v82
	v_max_f32_e32 v83, v83, v83
	v_max_f32_e32 v84, v84, v84
	v_max_f32_e32 v85, v85, v85
	v_max_f32_e32 v86, v86, v86
	v_max_f32_e32 v87, v87, v87
	v_max_f32_e32 v64, v64, v64
	v_max_f32_e32 v65, v65, v65
	v_max_f32_e32 v66, v66, v66
	v_max_f32_e32 v67, v67, v67
	v_max_f32_e32 v68, v68, v68
	v_max_f32_e32 v69, v69, v69
	v_max_f32_e32 v70, v70, v70
	v_max_f32_e32 v71, v71, v71
	v_max_f32_e32 v54, v54, v54
	v_max_f32_e32 v55, v55, v55
	v_max_f32_e32 v32, v32, v32
	v_max_f32_e32 v33, v33, v33
	v_max_f32_e32 v34, v34, v34
	v_max_f32_e32 v35, v35, v35
	v_max_f32_e32 v36, v36, v36
	v_max_f32_e32 v37, v37, v37
	v_max_f32_e32 v38, v38, v38
	v_max_f32_e32 v39, v39, v39
	v_max_f32_e32 v16, v16, v16
	v_max_f32_e32 v17, v17, v17
	v_max_f32_e32 v18, v18, v18
	v_max_f32_e32 v19, v19, v19
	v_max_f32_e32 v20, v20, v20
	v_max_f32_e32 v21, v21, v21
	v_max_f32_e32 v22, v22, v22
	v_max_f32_e32 v23, v23, v23
	ds_write2_b64 v52, v[0:1], v[2:3] offset0:88 offset1:90
	v_cvt_pk_bf16_f32 v0, v8, v9
	v_cvt_pk_bf16_f32 v1, v10, v11
	v_cvt_pk_bf16_f32 v2, v12, v13
	v_cvt_pk_bf16_f32 v3, v14, v15
	v_readlane_b32 s14, v254, 54
	v_max_f32_e32 v112, 0, v112
	v_max_f32_e32 v113, 0, v113
	v_max_f32_e32 v114, 0, v114
	v_max_f32_e32 v115, 0, v115
	v_max_f32_e32 v116, 0, v116
	v_max_f32_e32 v117, 0, v117
	v_max_f32_e32 v118, 0, v118
	v_max_f32_e32 v119, 0, v119
	v_max_f32_e32 v120, v120, v120
	v_max_f32_e32 v121, v121, v121
	v_max_f32_e32 v122, v122, v122
	v_max_f32_e32 v123, v123, v123
	v_max_f32_e32 v124, v124, v124
	v_max_f32_e32 v125, v125, v125
	v_max_f32_e32 v126, v126, v126
	v_max_f32_e32 v127, v127, v127
	v_max_f32_e32 v96, 0, v96
	v_max_f32_e32 v97, 0, v97
	v_max_f32_e32 v98, 0, v98
	v_max_f32_e32 v99, 0, v99
	v_max_f32_e32 v100, 0, v100
	v_max_f32_e32 v101, 0, v101
	v_max_f32_e32 v102, 0, v102
	v_max_f32_e32 v103, 0, v103
	v_max_f32_e32 v104, v104, v104
	v_max_f32_e32 v105, v105, v105
	v_max_f32_e32 v106, v106, v106
	v_max_f32_e32 v107, v107, v107
	v_max_f32_e32 v108, v108, v108
	v_max_f32_e32 v109, v109, v109
	v_max_f32_e32 v110, v110, v110
	v_max_f32_e32 v111, v111, v111
	v_max_f32_e32 v80, 0, v80
	v_max_f32_e32 v81, 0, v81
	v_max_f32_e32 v82, 0, v82
	v_max_f32_e32 v83, 0, v83
	v_max_f32_e32 v84, 0, v84
	v_max_f32_e32 v85, 0, v85
	v_max_f32_e32 v86, 0, v86
	v_max_f32_e32 v87, 0, v87
	v_max_f32_e32 v88, v88, v88
	v_max_f32_e32 v89, v89, v89
	v_max_f32_e32 v90, v90, v90
	v_max_f32_e32 v91, v91, v91
	v_max_f32_e32 v92, v92, v92
	v_max_f32_e32 v93, v93, v93
	v_max_f32_e32 v94, v94, v94
	v_max_f32_e32 v95, v95, v95
	v_max_f32_e32 v64, 0, v64
	v_max_f32_e32 v65, 0, v65
	v_max_f32_e32 v66, 0, v66
	v_max_f32_e32 v67, 0, v67
	v_max_f32_e32 v68, 0, v68
	v_max_f32_e32 v69, 0, v69
	v_max_f32_e32 v70, 0, v70
	v_max_f32_e32 v71, 0, v71
	v_max_f32_e32 v72, v72, v72
	v_max_f32_e32 v73, v73, v73
	v_max_f32_e32 v74, v74, v74
	v_max_f32_e32 v75, v75, v75
	v_max_f32_e32 v76, v76, v76
	v_max_f32_e32 v77, v77, v77
	v_max_f32_e32 v78, v78, v78
	v_max_f32_e32 v79, v79, v79
	v_max_f32_e32 v54, 0, v54
	v_max_f32_e32 v55, 0, v55
	v_max_f32_e32 v56, v56, v56
	v_max_f32_e32 v57, v57, v57
	v_max_f32_e32 v58, v58, v58
	v_max_f32_e32 v59, v59, v59
	v_max_f32_e32 v60, v60, v60
	v_max_f32_e32 v61, v61, v61
	v_max_f32_e32 v62, v62, v62
	v_max_f32_e32 v63, v63, v63
	v_max_f32_e32 v32, 0, v32
	v_max_f32_e32 v33, 0, v33
	v_max_f32_e32 v34, 0, v34
	v_max_f32_e32 v35, 0, v35
	v_max_f32_e32 v36, 0, v36
	v_max_f32_e32 v37, 0, v37
	v_max_f32_e32 v38, 0, v38
	v_max_f32_e32 v39, 0, v39
	v_max_f32_e32 v40, v40, v40
	v_max_f32_e32 v41, v41, v41
	v_max_f32_e32 v42, v42, v42
	v_max_f32_e32 v43, v43, v43
	v_max_f32_e32 v44, v44, v44
	v_max_f32_e32 v45, v45, v45
	v_max_f32_e32 v46, v46, v46
	v_max_f32_e32 v47, v47, v47
	v_max_f32_e32 v16, 0, v16
	v_max_f32_e32 v17, 0, v17
	v_max_f32_e32 v18, 0, v18
	v_max_f32_e32 v19, 0, v19
	v_max_f32_e32 v20, 0, v20
	v_max_f32_e32 v21, 0, v21
	v_max_f32_e32 v22, 0, v22
	v_max_f32_e32 v23, 0, v23
	v_max_f32_e32 v24, v24, v24
	v_max_f32_e32 v25, v25, v25
	v_max_f32_e32 v26, v26, v26
	v_max_f32_e32 v27, v27, v27
	v_max_f32_e32 v28, v28, v28
	v_max_f32_e32 v29, v29, v29
	v_max_f32_e32 v30, v30, v30
	v_max_f32_e32 v31, v31, v31
	ds_write2_b64 v52, v[0:1], v[2:3] offset0:92 offset1:94
	v_lshlrev_b32_e32 v0, 4, v156
	v_readlane_b32 s15, v254, 55
	s_add_u32 s4, s14, s4
	v_pk_mul_f32 v[112:113], v[112:113], v[112:113]
	v_pk_mul_f32 v[114:115], v[114:115], v[114:115]
	v_pk_mul_f32 v[116:117], v[116:117], v[116:117]
	v_pk_mul_f32 v[118:119], v[118:119], v[118:119]
	v_max_f32_e32 v120, 0, v120
	v_max_f32_e32 v121, 0, v121
	v_max_f32_e32 v122, 0, v122
	v_max_f32_e32 v123, 0, v123
	v_max_f32_e32 v124, 0, v124
	v_max_f32_e32 v125, 0, v125
	v_max_f32_e32 v126, 0, v126
	v_max_f32_e32 v127, 0, v127
	v_pk_mul_f32 v[96:97], v[96:97], v[96:97]
	v_pk_mul_f32 v[98:99], v[98:99], v[98:99]
	v_pk_mul_f32 v[100:101], v[100:101], v[100:101]
	v_pk_mul_f32 v[102:103], v[102:103], v[102:103]
	v_max_f32_e32 v104, 0, v104
	v_max_f32_e32 v105, 0, v105
	v_max_f32_e32 v106, 0, v106
	v_max_f32_e32 v107, 0, v107
	v_max_f32_e32 v108, 0, v108
	v_max_f32_e32 v109, 0, v109
	v_max_f32_e32 v110, 0, v110
	v_max_f32_e32 v111, 0, v111
	v_pk_mul_f32 v[80:81], v[80:81], v[80:81]
	v_pk_mul_f32 v[82:83], v[82:83], v[82:83]
	v_pk_mul_f32 v[84:85], v[84:85], v[84:85]
	v_pk_mul_f32 v[86:87], v[86:87], v[86:87]
	v_max_f32_e32 v88, 0, v88
	v_max_f32_e32 v89, 0, v89
	v_max_f32_e32 v90, 0, v90
	v_max_f32_e32 v91, 0, v91
	v_max_f32_e32 v92, 0, v92
	v_max_f32_e32 v93, 0, v93
	v_max_f32_e32 v94, 0, v94
	v_max_f32_e32 v95, 0, v95
	v_pk_mul_f32 v[64:65], v[64:65], v[64:65]
	v_pk_mul_f32 v[66:67], v[66:67], v[66:67]
	v_pk_mul_f32 v[68:69], v[68:69], v[68:69]
	v_pk_mul_f32 v[70:71], v[70:71], v[70:71]
	v_max_f32_e32 v72, 0, v72
	v_max_f32_e32 v73, 0, v73
	v_max_f32_e32 v74, 0, v74
	v_max_f32_e32 v75, 0, v75
	v_max_f32_e32 v76, 0, v76
	v_max_f32_e32 v77, 0, v77
	v_max_f32_e32 v78, 0, v78
	v_max_f32_e32 v79, 0, v79
	v_pk_mul_f32 v[54:55], v[54:55], v[54:55]
	v_max_f32_e32 v56, 0, v56
	v_max_f32_e32 v57, 0, v57
	v_max_f32_e32 v58, 0, v58
	v_max_f32_e32 v59, 0, v59
	v_max_f32_e32 v60, 0, v60
	v_max_f32_e32 v61, 0, v61
	v_max_f32_e32 v62, 0, v62
	v_max_f32_e32 v63, 0, v63
	v_pk_mul_f32 v[32:33], v[32:33], v[32:33]
	v_pk_mul_f32 v[34:35], v[34:35], v[34:35]
	v_pk_mul_f32 v[36:37], v[36:37], v[36:37]
	v_pk_mul_f32 v[38:39], v[38:39], v[38:39]
	v_max_f32_e32 v40, 0, v40
	v_max_f32_e32 v41, 0, v41
	v_max_f32_e32 v42, 0, v42
	v_max_f32_e32 v43, 0, v43
	v_max_f32_e32 v44, 0, v44
	v_max_f32_e32 v45, 0, v45
	v_max_f32_e32 v46, 0, v46
	v_max_f32_e32 v47, 0, v47
	v_pk_mul_f32 v[16:17], v[16:17], v[16:17]
	v_pk_mul_f32 v[18:19], v[18:19], v[18:19]
	v_pk_mul_f32 v[20:21], v[20:21], v[20:21]
	v_pk_mul_f32 v[22:23], v[22:23], v[22:23]
	v_max_f32_e32 v24, 0, v24
	v_max_f32_e32 v25, 0, v25
	v_max_f32_e32 v26, 0, v26
	v_max_f32_e32 v27, 0, v27
	v_max_f32_e32 v28, 0, v28
	v_max_f32_e32 v29, 0, v29
	v_max_f32_e32 v30, 0, v30
	v_max_f32_e32 v31, 0, v31
	v_and_b32_e32 v190, 0x1f0, v0
	s_addc_u32 s5, s15, s5
	v_ashrrev_i32_e32 v2, 5, v156
	v_pk_mul_f32 v[120:121], v[120:121], v[120:121]
	v_pk_mul_f32 v[122:123], v[122:123], v[122:123]
	v_pk_mul_f32 v[124:125], v[124:125], v[124:125]
	v_pk_mul_f32 v[126:127], v[126:127], v[126:127]
	v_cvt_pk_bf16_f32 v112, v112, v113
	v_cvt_pk_bf16_f32 v113, v114, v115
	v_cvt_pk_bf16_f32 v114, v116, v117
	v_cvt_pk_bf16_f32 v115, v118, v119
	v_pk_mul_f32 v[104:105], v[104:105], v[104:105]
	v_pk_mul_f32 v[106:107], v[106:107], v[106:107]
	v_pk_mul_f32 v[108:109], v[108:109], v[108:109]
	v_pk_mul_f32 v[110:111], v[110:111], v[110:111]
	v_cvt_pk_bf16_f32 v96, v96, v97
	v_cvt_pk_bf16_f32 v97, v98, v99
	v_cvt_pk_bf16_f32 v98, v100, v101
	v_cvt_pk_bf16_f32 v99, v102, v103
	v_pk_mul_f32 v[88:89], v[88:89], v[88:89]
	v_pk_mul_f32 v[90:91], v[90:91], v[90:91]
	v_pk_mul_f32 v[92:93], v[92:93], v[92:93]
	v_pk_mul_f32 v[94:95], v[94:95], v[94:95]
	v_cvt_pk_bf16_f32 v80, v80, v81
	v_cvt_pk_bf16_f32 v81, v82, v83
	v_cvt_pk_bf16_f32 v82, v84, v85
	v_cvt_pk_bf16_f32 v83, v86, v87
	v_pk_mul_f32 v[72:73], v[72:73], v[72:73]
	v_pk_mul_f32 v[74:75], v[74:75], v[74:75]
	v_pk_mul_f32 v[76:77], v[76:77], v[76:77]
	v_pk_mul_f32 v[78:79], v[78:79], v[78:79]
	v_cvt_pk_bf16_f32 v64, v64, v65
	v_cvt_pk_bf16_f32 v65, v66, v67
	v_cvt_pk_bf16_f32 v66, v68, v69
	v_cvt_pk_bf16_f32 v67, v70, v71
	v_pk_mul_f32 v[56:57], v[56:57], v[56:57]
	v_pk_mul_f32 v[58:59], v[58:59], v[58:59]
	v_pk_mul_f32 v[60:61], v[60:61], v[60:61]
	v_pk_mul_f32 v[62:63], v[62:63], v[62:63]
	v_cvt_pk_bf16_f32 v51, v54, v55
	v_pk_mul_f32 v[40:41], v[40:41], v[40:41]
	v_pk_mul_f32 v[42:43], v[42:43], v[42:43]
	v_pk_mul_f32 v[44:45], v[44:45], v[44:45]
	v_pk_mul_f32 v[46:47], v[46:47], v[46:47]
	v_cvt_pk_bf16_f32 v32, v32, v33
	v_cvt_pk_bf16_f32 v33, v34, v35
	v_cvt_pk_bf16_f32 v34, v36, v37
	v_cvt_pk_bf16_f32 v35, v38, v39
	v_pk_mul_f32 v[24:25], v[24:25], v[24:25]
	v_pk_mul_f32 v[26:27], v[26:27], v[26:27]
	v_pk_mul_f32 v[28:29], v[28:29], v[28:29]
	v_pk_mul_f32 v[30:31], v[30:31], v[30:31]
	v_cvt_pk_bf16_f32 v16, v16, v17
	v_cvt_pk_bf16_f32 v17, v18, v19
	v_cvt_pk_bf16_f32 v18, v20, v21
	v_cvt_pk_bf16_f32 v19, v22, v23
	v_lshl_add_u64 v[4:5], s[4:5], 0, v[190:191]
	v_mad_u64_u32 v[0:1], s[4:5], v2, s18, v[190:191]
	ds_write2_b64 v128, v[112:113], v[114:115] offset1:2
	v_cvt_pk_bf16_f32 v112, v120, v121
	v_cvt_pk_bf16_f32 v113, v122, v123
	v_cvt_pk_bf16_f32 v114, v124, v125
	v_cvt_pk_bf16_f32 v115, v126, v127
	ds_write2_b64 v128, v[96:97], v[98:99] offset0:8 offset1:10
	v_cvt_pk_bf16_f32 v96, v104, v105
	v_cvt_pk_bf16_f32 v97, v106, v107
	v_cvt_pk_bf16_f32 v98, v108, v109
	v_cvt_pk_bf16_f32 v99, v110, v111
	ds_write2_b64 v128, v[80:81], v[82:83] offset0:16 offset1:18
	v_cvt_pk_bf16_f32 v80, v88, v89
	v_cvt_pk_bf16_f32 v81, v90, v91
	v_cvt_pk_bf16_f32 v82, v92, v93
	v_cvt_pk_bf16_f32 v83, v94, v95
	ds_write2_b64 v128, v[64:65], v[66:67] offset0:24 offset1:26
	v_cvt_pk_bf16_f32 v64, v72, v73
	v_cvt_pk_bf16_f32 v65, v74, v75
	v_cvt_pk_bf16_f32 v66, v76, v77
	v_cvt_pk_bf16_f32 v67, v78, v79
	ds_write2_b64 v52, v[48:49], v[50:51] offset0:64 offset1:66
	v_cvt_pk_bf16_f32 v48, v56, v57
	v_cvt_pk_bf16_f32 v49, v58, v59
	v_cvt_pk_bf16_f32 v50, v60, v61
	v_cvt_pk_bf16_f32 v51, v62, v63
	ds_write2_b64 v52, v[32:33], v[34:35] offset0:72 offset1:74
	v_cvt_pk_bf16_f32 v32, v40, v41
	v_cvt_pk_bf16_f32 v33, v42, v43
	v_cvt_pk_bf16_f32 v34, v44, v45
	v_cvt_pk_bf16_f32 v35, v46, v47
	ds_write2_b64 v52, v[16:17], v[18:19] offset0:80 offset1:82
	v_cvt_pk_bf16_f32 v16, v24, v25
	v_cvt_pk_bf16_f32 v17, v26, v27
	v_cvt_pk_bf16_f32 v18, v28, v29
	v_cvt_pk_bf16_f32 v19, v30, v31
	v_add_u32_e32 v1, s40, v2
	ds_write2_b64 v128, v[112:113], v[114:115] offset0:4 offset1:6
	ds_write2_b64 v128, v[96:97], v[98:99] offset0:12 offset1:14
	ds_write2_b64 v128, v[80:81], v[82:83] offset0:20 offset1:22
	ds_write2_b64 v128, v[64:65], v[66:67] offset0:28 offset1:30
	ds_write2_b64 v52, v[48:49], v[50:51] offset0:68 offset1:70
	ds_write2_b64 v52, v[32:33], v[34:35] offset0:76 offset1:78
	ds_write2_b64 v52, v[16:17], v[18:19] offset0:84 offset1:86
	s_waitcnt lgkmcnt(0)
	s_barrier
	v_mad_i64_i32 v[6:7], s[4:5], v1, s7, v[4:5]
	ds_read_b128 v[0:3], v0
	s_add_i32 s2, s2, 1
	s_waitcnt lgkmcnt(0)
	global_store_dwordx4 v[6:7], v[0:3], off
	s_nop 1
	v_add_u32_e32 v0, 0x100, v156
	v_ashrrev_i32_e32 v2, 5, v0
	v_mad_u64_u32 v[0:1], s[4:5], v2, s18, v[190:191]
	v_add_u32_e32 v1, s40, v2
	v_mad_i64_i32 v[6:7], s[4:5], v1, s7, v[4:5]
	ds_read_b128 v[0:3], v0
	s_waitcnt lgkmcnt(0)
	global_store_dwordx4 v[6:7], v[0:3], off
	s_nop 1
	v_add_u32_e32 v0, 0x200, v156
	v_ashrrev_i32_e32 v2, 5, v0
	v_mad_u64_u32 v[0:1], s[4:5], v2, s18, v[190:191]
	v_add_u32_e32 v1, s40, v2
	v_mad_i64_i32 v[6:7], s[4:5], v1, s7, v[4:5]
	ds_read_b128 v[0:3], v0
	s_waitcnt lgkmcnt(0)
	global_store_dwordx4 v[6:7], v[0:3], off
	s_nop 1
	v_add_u32_e32 v0, 0x300, v156
	v_ashrrev_i32_e32 v2, 5, v0
	v_mad_u64_u32 v[0:1], s[4:5], v2, s18, v[190:191]
	v_add_u32_e32 v1, s40, v2
	v_mad_i64_i32 v[6:7], s[4:5], v1, s7, v[4:5]
	ds_read_b128 v[0:3], v0
	s_waitcnt lgkmcnt(0)
	global_store_dwordx4 v[6:7], v[0:3], off
	s_nop 1
	v_add_u32_e32 v0, 0x400, v156
	v_ashrrev_i32_e32 v2, 5, v0
	v_mad_u64_u32 v[0:1], s[4:5], v2, s18, v[190:191]
	v_add_u32_e32 v1, s40, v2
	v_mad_i64_i32 v[6:7], s[4:5], v1, s7, v[4:5]
	ds_read_b128 v[0:3], v0
	s_waitcnt lgkmcnt(0)
	global_store_dwordx4 v[6:7], v[0:3], off
	s_nop 1
	v_add_u32_e32 v0, 0x500, v156
	v_ashrrev_i32_e32 v2, 5, v0
	v_mad_u64_u32 v[0:1], s[4:5], v2, s18, v[190:191]
	v_add_u32_e32 v1, s40, v2
	v_mad_i64_i32 v[6:7], s[4:5], v1, s7, v[4:5]
	ds_read_b128 v[0:3], v0
	s_waitcnt lgkmcnt(0)
	global_store_dwordx4 v[6:7], v[0:3], off
	s_nop 1
	v_add_u32_e32 v0, 0x600, v156
	v_ashrrev_i32_e32 v2, 5, v0
	v_mad_u64_u32 v[0:1], s[4:5], v2, s18, v[190:191]
	v_add_u32_e32 v1, s40, v2
	v_mad_i64_i32 v[6:7], s[4:5], v1, s7, v[4:5]
	ds_read_b128 v[0:3], v0
	s_waitcnt lgkmcnt(0)
	global_store_dwordx4 v[6:7], v[0:3], off
	s_nop 1
	v_add_u32_e32 v0, 0x700, v156
	v_ashrrev_i32_e32 v2, 5, v0
	v_mad_u64_u32 v[0:1], s[4:5], v2, s18, v[190:191]
	v_add_u32_e32 v1, s40, v2
	v_mad_i64_i32 v[6:7], s[4:5], v1, s7, v[4:5]
	ds_read_b128 v[0:3], v0
	s_waitcnt lgkmcnt(0)
	global_store_dwordx4 v[6:7], v[0:3], off
	s_nop 1
	v_add_u32_e32 v0, 0x800, v156
	v_ashrrev_i32_e32 v2, 5, v0
	v_mad_u64_u32 v[0:1], s[4:5], v2, s18, v[190:191]
	v_add_u32_e32 v1, s40, v2
	v_mad_i64_i32 v[6:7], s[4:5], v1, s7, v[4:5]
	ds_read_b128 v[0:3], v0
	s_waitcnt lgkmcnt(0)
	global_store_dwordx4 v[6:7], v[0:3], off
	s_nop 1
	v_add_u32_e32 v0, 0x900, v156
	v_ashrrev_i32_e32 v2, 5, v0
	v_mad_u64_u32 v[0:1], s[4:5], v2, s18, v[190:191]
	v_add_u32_e32 v1, s40, v2
	v_mad_i64_i32 v[6:7], s[4:5], v1, s7, v[4:5]
	ds_read_b128 v[0:3], v0
	s_waitcnt lgkmcnt(0)
	global_store_dwordx4 v[6:7], v[0:3], off
	s_nop 1
	v_add_u32_e32 v0, 0xa00, v156
	v_ashrrev_i32_e32 v2, 5, v0
	v_mad_u64_u32 v[0:1], s[4:5], v2, s18, v[190:191]
	v_add_u32_e32 v1, s40, v2
	v_mad_i64_i32 v[6:7], s[4:5], v1, s7, v[4:5]
	ds_read_b128 v[0:3], v0
	s_waitcnt lgkmcnt(0)
	global_store_dwordx4 v[6:7], v[0:3], off
	s_nop 1
	v_add_u32_e32 v0, 0xb00, v156
	v_ashrrev_i32_e32 v2, 5, v0
	v_mad_u64_u32 v[0:1], s[4:5], v2, s18, v[190:191]
	v_add_u32_e32 v1, s40, v2
	v_mad_i64_i32 v[6:7], s[4:5], v1, s7, v[4:5]
	ds_read_b128 v[0:3], v0
	s_waitcnt lgkmcnt(0)
	global_store_dwordx4 v[6:7], v[0:3], off
	s_nop 1
	v_add_u32_e32 v0, 0xc00, v156
	v_ashrrev_i32_e32 v2, 5, v0
	v_mad_u64_u32 v[0:1], s[4:5], v2, s18, v[190:191]
	v_add_u32_e32 v1, s40, v2
	v_mad_i64_i32 v[6:7], s[4:5], v1, s7, v[4:5]
	ds_read_b128 v[0:3], v0
	s_waitcnt lgkmcnt(0)
	global_store_dwordx4 v[6:7], v[0:3], off
	s_nop 1
	v_add_u32_e32 v0, 0xd00, v156
	v_ashrrev_i32_e32 v2, 5, v0
	v_mad_u64_u32 v[0:1], s[4:5], v2, s18, v[190:191]
	v_add_u32_e32 v1, s40, v2
	v_mad_i64_i32 v[6:7], s[4:5], v1, s7, v[4:5]
	ds_read_b128 v[0:3], v0
	s_waitcnt lgkmcnt(0)
	global_store_dwordx4 v[6:7], v[0:3], off
	s_nop 1
	v_add_u32_e32 v0, 0xe00, v156
	v_ashrrev_i32_e32 v2, 5, v0
	v_mad_u64_u32 v[0:1], s[4:5], v2, s18, v[190:191]
	v_add_u32_e32 v1, s40, v2
	v_mad_i64_i32 v[6:7], s[4:5], v1, s7, v[4:5]
	ds_read_b128 v[0:3], v0
	s_waitcnt lgkmcnt(0)
	global_store_dwordx4 v[6:7], v[0:3], off
	s_nop 1
	v_add_u32_e32 v0, 0xf00, v156
	v_ashrrev_i32_e32 v2, 5, v0
	v_mad_u64_u32 v[0:1], s[4:5], v2, s18, v[190:191]
	v_add_u32_e32 v1, s40, v2
	v_mad_i64_i32 v[4:5], s[4:5], v1, s7, v[4:5]
	ds_read_b128 v[0:3], v0
	s_mov_b64 s[4:5], 0
	s_waitcnt lgkmcnt(0)
	global_store_dwordx4 v[4:5], v[0:3], off
	s_barrier
	s_branch .LBB0_1060
